# two-point early write-back: buffer_wbl2 at 75 percent and at n-1 arrivals per XCD
# baseline (speedup 1.0000x reference)
; __device__ __forceinline__ unsigned xb_ld(unsigned* p)              { return __hip_atomic_load(p, __ATOMIC_RELAXED, __HIP_MEMORY_SCOPE_AGENT); }
; __device__ __forceinline__ unsigned xb_add(unsigned* p, unsigned v) { return __hip_atomic_fetch_add(p, v, __ATOMIC_RELAXED, __HIP_MEMORY_SCOPE_AGENT); }
; #define XB_SPIN(cond, bar) do { unsigned _sp = 0; while (cond) { __builtin_amdgcn_s_sleep(0); \
;     if ((++_sp & 255u) == 0u) { if (xb_ld(&(bar)[XB_TMO])) break; if (_sp > XB_SPIN_CAP) { atomicAdd(&(bar)[XB_TMO], 1u); break; } } } } while (0)
; __device__ __forceinline__ void xcd_barrier(const XcdBarrier& b) {
;     ...
;         const unsigned old = xb_add(&bar[XB_XSUB(b.x)], 1u);
;         const unsigned gen = old / nloc;
;         if (old + 1u == (gen + 1u) * nloc) {
;     ...
;         } else {
;             XB_SPIN(xb_ld(&bar[XB_XGEN(b.x)]) == gen, bar);
.LBB0_155:
	s_or_b64 exec, exec, s[0:1]
	v_cvt_f32_u32_e32 v4, v2
	s_waitcnt vmcnt(0)
	v_readfirstlane_b32 s0, v3
	v_sub_u32_e32 v3, 0, v2
	v_rcp_iflag_f32_e32 v4, v4
	v_add_u32_e32 v5, s0, v1
	v_mul_f32_e32 v4, 0x4f7ffffe, v4
	v_cvt_u32_f32_e32 v4, v4
	v_mul_lo_u32 v1, v3, v4
	v_mul_hi_u32 v1, v4, v1
	v_add_u32_e32 v1, v4, v1
	v_mul_hi_u32 v1, v5, v1
	v_mul_lo_u32 v3, v1, v2
	v_sub_u32_e32 v3, v5, v3
	v_add_u32_e32 v4, 1, v1
	v_cmp_ge_u32_e32 vcc, v3, v2
	s_nop 1
	v_cndmask_b32_e32 v1, v1, v4, vcc
	v_sub_u32_e32 v4, v3, v2
	v_cndmask_b32_e32 v3, v3, v4, vcc
	v_add_u32_e32 v4, 1, v1
	v_cmp_ge_u32_e32 vcc, v3, v2
	v_add_u32_e32 v3, 1, v5
	s_nop 0
	v_cndmask_b32_e32 v1, v1, v4, vcc
	v_mul_lo_u32 v4, v2, v1
	v_add_u32_e32 v2, v4, v2
	v_cmp_ne_u32_e32 vcc, v3, v2
	s_and_saveexec_b64 s[0:1], vcc
	s_xor_b64 s[0:1], exec, s[0:1]
	s_cbranch_execz .LBB0_169
	v_readlane_b32 s2, v252, 7
	v_readlane_b32 s3, v252, 8
	s_waitcnt lgkmcnt(0)
	v_mad_u32_u24 v1, v0, v1, v0
	v_sub_u32_e32 v3, v3, v4
	v_sub_u32_e32 v4, v2, v4
	v_lshlrev_b32_e32 v5, 2, v4
	v_lshlrev_b32_e32 v3, 2, v3
	v_add_u32_e32 v5, -4, v5
	v_mul_u32_u24_e32 v4, 3, v4
	v_cmp_eq_u32_e32 vcc, v3, v5
	s_cbranch_vccnz .Lewb_do0
	v_cmp_eq_u32_e32 vcc, v3, v4
	s_cbranch_vccz .Lewb_skip0
